# attention LDS tile loop: all eight K-fragment ds_reads of the QK block issued up front into dead registers, counted lgkmcnt waits
# speedup vs baseline: 1.0019x; 1.0019x over previous
; #define LAS __attribute__((address_space(3)))
; __device__ __forceinline__ void attn_tile_scores(AttnState& st, u32x4 (&pw)[4], const bf16x8 (&qf)[4], const bf16x8 (&kf)[2][4], int kv0, int P0, int pq, int hi) {
;     f32x16 s0 = {}, s1 = {};
; #pragma unroll
;     for (int d0 = 0; d0 < 4; ++d0) { s0 = __builtin_amdgcn_mfma_f32_32x32x16_bf16(kf[0][d0], qf[d0], s0, 0, 0, 0); s1 = __builtin_amdgcn_mfma_f32_32x32x16_bf16(kf[1][d0], qf[d0], s1, 0, 0, 0); }
;     const int kb = kv0 + 32 * hi;
;     if (kv0 + 64 > P0) { const int lim = pq - kb - 1;
; #pragma unroll
;         for (int r = 0; r < 16; ++r) { const int m0 = lim - r, m1 = lim - 16 - r;
;             s0[r] = __builtin_fmaf((float)(m0 < 0 ? m0 : 0), 1e30f, s0[r]); s1[r] = __builtin_fmaf((float)(m1 < 0 ? m1 : 0), 1e30f, s1[r]); } }
; __device__ __forceinline__ void sb_attn_wave(LAS unsigned char* lds, int Tlo, const bf16* __restrict__ u, const bf16* __restrict__ um, const bf16* __restrict__ vT, const bf16* __restrict__ vTm, ...
;     ...
;             for (int d0 = 0; d0 < 4; ++d0) kf[hf][d0] = *(const LAS bf16x8*)(kbase + so + hf * 32 * AT_PITCH + d0 * 32);
.LBB0_281:
	v_add_u32_e32 v6, v10, v195
	ds_read_b128 v[2:5], v6
	ds_read_b128 v[154:157], v6 offset:4608
	ds_read_b128 v[158:161], v6 offset:32
	ds_read_b128 v[162:165], v6 offset:4640
	ds_read_b128 v[166:169], v6 offset:64
	ds_read_b128 v[218:221], v6 offset:4672
	ds_read_b128 v[222:225], v6 offset:96
	ds_read_b128 v[226:229], v6 offset:4704
	s_cmp_le_i32 s41, s53
	s_waitcnt vmcnt(17) lgkmcnt(7)
	v_mfma_f32_32x32x16_bf16 v[64:79], v[2:5], v[136:139], 0
	s_waitcnt lgkmcnt(6)
	v_mfma_f32_32x32x16_bf16 v[48:63], v[154:157], v[136:139], 0
	s_waitcnt vmcnt(16) lgkmcnt(5)
	v_mfma_f32_32x32x16_bf16 v[64:79], v[158:161], v[140:143], v[64:79]
	s_waitcnt lgkmcnt(4)
	v_mfma_f32_32x32x16_bf16 v[48:63], v[162:165], v[140:143], v[48:63]
	s_waitcnt vmcnt(15) lgkmcnt(3)
	v_mfma_f32_32x32x16_bf16 v[64:79], v[166:169], v[144:147], v[64:79]
	s_waitcnt lgkmcnt(2)
	v_mfma_f32_32x32x16_bf16 v[48:63], v[218:221], v[144:147], v[48:63]
	s_waitcnt vmcnt(14) lgkmcnt(1)
	v_mfma_f32_32x32x16_bf16 v[64:79], v[222:225], v[148:151], v[64:79]
	s_waitcnt lgkmcnt(0)
	v_mfma_f32_32x32x16_bf16 v[48:63], v[226:229], v[148:151], v[48:63]
	s_nop 0
	s_cbranch_scc1 .LBB0_280
	v_min_i32_e32 v3, 16, v0
	v_add_u32_e32 v4, -16, v3
	v_min_i32_e32 v3, 1, v0
	v_min_i32_e32 v2, 0, v0
	v_add_u32_e32 v3, -1, v3
	v_cvt_f32_i32_e32 v2, v2
	v_cvt_f32_i32_e32 v3, v3
	v_subrev_u32_e32 v5, 17, v0
	v_pk_fma_f32 v[64:65], v[2:3], s[72:73], v[64:65] op_sel_hi:[1,0,1]
	v_min_i32_e32 v2, 0, v5
	v_cvt_f32_i32_e32 v3, v2
	v_cvt_f32_i32_e32 v2, v4
	v_pk_fma_f32 v[48:49], v[2:3], s[72:73], v[48:49] op_sel_hi:[1,0,1]
	v_subrev_u32_e32 v2, 18, v0
	v_min_i32_e32 v3, 2, v0
	v_add_u32_e32 v3, -2, v3
	v_min_i32_e32 v2, 0, v2
	v_cvt_f32_i32_e32 v3, v3
	v_cvt_f32_i32_e32 v2, v2
	v_fmamk_f32 v66, v3, 0x7149f2ca, v66
	v_fmamk_f32 v50, v2, 0x7149f2ca, v50
	v_subrev_u32_e32 v2, 19, v0
	v_min_i32_e32 v3, 3, v0
	v_add_u32_e32 v3, -3, v3
	v_min_i32_e32 v2, 0, v2
	v_cvt_f32_i32_e32 v3, v3
	v_cvt_f32_i32_e32 v2, v2
	v_fmamk_f32 v67, v3, 0x7149f2ca, v67
	v_fmamk_f32 v51, v2, 0x7149f2ca, v51
	v_subrev_u32_e32 v2, 20, v0
	v_min_i32_e32 v3, 4, v0
	v_add_u32_e32 v3, -4, v3
	v_min_i32_e32 v2, 0, v2
	v_cvt_f32_i32_e32 v3, v3
	v_cvt_f32_i32_e32 v2, v2
	v_fmamk_f32 v68, v3, 0x7149f2ca, v68
	v_fmamk_f32 v52, v2, 0x7149f2ca, v52
	v_subrev_u32_e32 v2, 21, v0
	v_min_i32_e32 v3, 5, v0
	v_add_u32_e32 v3, -5, v3
	v_min_i32_e32 v2, 0, v2
	v_cvt_f32_i32_e32 v3, v3
	v_cvt_f32_i32_e32 v2, v2
	v_fmamk_f32 v69, v3, 0x7149f2ca, v69
	v_fmamk_f32 v53, v2, 0x7149f2ca, v53
	v_subrev_u32_e32 v2, 22, v0
	v_min_i32_e32 v3, 6, v0
	v_add_u32_e32 v3, -6, v3
	v_min_i32_e32 v2, 0, v2
	v_cvt_f32_i32_e32 v3, v3
	v_cvt_f32_i32_e32 v2, v2
	v_fmamk_f32 v70, v3, 0x7149f2ca, v70
	v_fmamk_f32 v54, v2, 0x7149f2ca, v54
	v_subrev_u32_e32 v2, 23, v0
	v_min_i32_e32 v3, 7, v0
	v_add_u32_e32 v3, -7, v3
	v_min_i32_e32 v2, 0, v2
	v_cvt_f32_i32_e32 v3, v3
	v_cvt_f32_i32_e32 v2, v2
	v_fmamk_f32 v71, v3, 0x7149f2ca, v71
	v_fmamk_f32 v55, v2, 0x7149f2ca, v55
	v_subrev_u32_e32 v2, 24, v0
	v_min_i32_e32 v3, 8, v0
	v_add_u32_e32 v3, -8, v3
	v_min_i32_e32 v2, 0, v2
	v_cvt_f32_i32_e32 v3, v3
	v_cvt_f32_i32_e32 v2, v2
	v_fmamk_f32 v72, v3, 0x7149f2ca, v72
	v_fmamk_f32 v56, v2, 0x7149f2ca, v56
	v_subrev_u32_e32 v2, 25, v0
	v_min_i32_e32 v3, 9, v0
	v_add_u32_e32 v3, -9, v3
	v_min_i32_e32 v2, 0, v2
	v_cvt_f32_i32_e32 v3, v3
	v_cvt_f32_i32_e32 v2, v2
	v_fmamk_f32 v73, v3, 0x7149f2ca, v73
	v_fmamk_f32 v57, v2, 0x7149f2ca, v57
	v_subrev_u32_e32 v2, 26, v0
	v_min_i32_e32 v3, 10, v0
	v_add_u32_e32 v3, -10, v3
	v_min_i32_e32 v2, 0, v2
	v_cvt_f32_i32_e32 v3, v3
	v_cvt_f32_i32_e32 v2, v2
	v_fmamk_f32 v74, v3, 0x7149f2ca, v74
	v_fmamk_f32 v58, v2, 0x7149f2ca, v58
	v_subrev_u32_e32 v2, 27, v0
	v_min_i32_e32 v3, 11, v0
	v_add_u32_e32 v3, -11, v3
	v_min_i32_e32 v2, 0, v2
	v_cvt_f32_i32_e32 v3, v3
	v_cvt_f32_i32_e32 v2, v2
	v_fmamk_f32 v75, v3, 0x7149f2ca, v75
	v_fmamk_f32 v59, v2, 0x7149f2ca, v59
	v_subrev_u32_e32 v2, 28, v0
	v_min_i32_e32 v3, 12, v0
	v_add_u32_e32 v3, -12, v3
	v_min_i32_e32 v2, 0, v2
	v_cvt_f32_i32_e32 v3, v3
	v_cvt_f32_i32_e32 v2, v2
	v_fmamk_f32 v76, v3, 0x7149f2ca, v76
	v_fmamk_f32 v60, v2, 0x7149f2ca, v60
	v_subrev_u32_e32 v2, 29, v0
	v_min_i32_e32 v3, 13, v0
	v_add_u32_e32 v3, -13, v3
	v_min_i32_e32 v2, 0, v2
	v_cvt_f32_i32_e32 v3, v3
	v_cvt_f32_i32_e32 v2, v2
	v_fmamk_f32 v77, v3, 0x7149f2ca, v77
	v_fmamk_f32 v61, v2, 0x7149f2ca, v61
	v_subrev_u32_e32 v2, 30, v0
	v_min_i32_e32 v3, 14, v0
	v_add_u32_e32 v3, -14, v3
	v_min_i32_e32 v2, 0, v2
	v_cvt_f32_i32_e32 v3, v3
	v_cvt_f32_i32_e32 v2, v2
	v_fmamk_f32 v78, v3, 0x7149f2ca, v78
	v_fmamk_f32 v62, v2, 0x7149f2ca, v62
	v_subrev_u32_e32 v2, 31, v0
	v_min_i32_e32 v3, 15, v0
	v_add_u32_e32 v3, -15, v3
	v_min_i32_e32 v2, 0, v2
	v_cvt_f32_i32_e32 v3, v3
	v_cvt_f32_i32_e32 v2, v2
	v_fmac_f32_e32 v79, 0x7149f2ca, v3
	v_fmac_f32_e32 v63, 0x7149f2ca, v2
	s_branch .LBB0_280
